# grid barrier: non-leader workgroups issue their L1 invalidate before spinning on the release flag (no data loads can enter L1 while waiting); the XCD leader completes its invalidate before releasing;
# speedup vs baseline: 1.0086x; 1.0086x over previous
.LBB0_1154:
	s_or_b64 exec, exec, s[20:21]
	v_cvt_f32_u32_e32 v5, v3
	s_waitcnt vmcnt(0)
	v_readfirstlane_b32 s20, v4
	v_sub_u32_e32 v4, 0, v3
	v_rcp_iflag_f32_e32 v5, v5
	v_add_u32_e32 v6, s20, v0
	v_mul_f32_e32 v5, 0x4f7ffffe, v5
	v_cvt_u32_f32_e32 v5, v5
	v_mul_lo_u32 v0, v4, v5
	v_mul_hi_u32 v0, v5, v0
	v_add_u32_e32 v0, v5, v0
	v_mul_hi_u32 v0, v6, v0
	v_mul_lo_u32 v4, v0, v3
	v_sub_u32_e32 v4, v6, v4
	v_add_u32_e32 v5, 1, v0
	v_cmp_ge_u32_e32 vcc, v4, v3
	s_nop 1
	v_cndmask_b32_e32 v0, v0, v5, vcc
	v_sub_u32_e32 v5, v4, v3
	v_cndmask_b32_e32 v4, v4, v5, vcc
	v_add_u32_e32 v5, 1, v0
	v_cmp_ge_u32_e32 vcc, v4, v3
	v_add_u32_e32 v4, 1, v6
	s_nop 0
	v_cndmask_b32_e32 v0, v0, v5, vcc
	v_mul_lo_u32 v5, v3, v0
	v_add_u32_e32 v3, v5, v3
	v_cmp_ne_u32_e32 vcc, v4, v3
	s_and_saveexec_b64 s[20:21], vcc
	s_xor_b64 s[20:21], exec, s[20:21]
	s_cbranch_execz .LBB0_1168
	v_readlane_b32 s4, v253, 0
	v_readlane_b32 s5, v253, 1
	s_waitcnt lgkmcnt(0)
	s_nop 3
	buffer_inv sc1
	global_load_dword v2, v1, s[4:5] sc1
	s_waitcnt vmcnt(0)
	v_cmp_eq_u32_e32 vcc, v2, v0
	s_and_saveexec_b64 s[22:23], vcc
	s_cbranch_execz .LBB0_1167
	s_mov_b32 s44, 1
	s_mov_b64 s[24:25], 0
	s_branch .LBB0_1158

.LBB0_1167:
	s_or_b64 exec, exec, s[22:23]
	s_waitcnt vmcnt(0)
	s_waitcnt vmcnt(0)

.LBB0_1185:
	s_or_b64 exec, exec, s[20:21]
	s_mov_b64 s[20:21], exec
	v_mbcnt_lo_u32_b32 v0, s20, 0
	v_mbcnt_hi_u32_b32 v0, s21, v0
	v_cmp_eq_u32_e32 vcc, 0, v0
	s_waitcnt vmcnt(0)
	buffer_inv sc1
	s_waitcnt vmcnt(0)
	s_and_saveexec_b64 s[22:23], vcc
	s_cbranch_execz .LBB0_1187
	s_bcnt1_i32_b64 s20, s[20:21]
	v_readlane_b32 s4, v253, 0
	v_mov_b32_e32 v0, s20
	v_readlane_b32 s5, v253, 1
	s_nop 4
	global_atomic_add v1, v0, s[4:5]
